# FoX attention pass prologue: gate loads, Q loads and tile DMA in one memory round trip (was three)
# baseline (speedup 1.0000x reference)
.LBB0_1484:
	s_mov_b32 m0, s50
	s_and_b64 s[20:21], s[38:39], exec
	s_barrier
	global_load_lds_dwordx4 v[158:159], off
	s_mov_b32 m0, s53
	s_cselect_b32 s84, s64, s63
	global_load_lds_dwordx4 v[160:161], off
	s_add_i32 m0, s50, 0x4000
	s_add_i32 s20, s84, 0x100
	global_load_lds_dwordx4 v[162:163], off
	s_mov_b32 m0, s54
	v_cmp_gt_i32_e64 s[20:21], s20, v156
	global_load_lds_dwordx4 v[164:165], off
	s_mov_b32 m0, s55
	v_mov_b32_e32 v1, 0
	global_load_lds_dwordx4 v[166:167], off
	s_mov_b32 m0, s58
	v_mov_b32_e32 v2, 0
	global_load_lds_dwordx4 v[168:169], off
	s_mov_b32 m0, s59
	s_nop 0
	global_load_lds_dwordx4 v[170:171], off
	s_mov_b32 m0, s60
	s_nop 0
	global_load_lds_dwordx4 v[172:173], off
	s_add_u32 s100, s76, s84
	s_addc_u32 s101, s77, 0
	s_lshl_b64 s[100:101], s[100:101], 12
	s_add_u32 s100, s65, s100
	s_addc_u32 s101, s66, s101
	v_mov_b32_e32 v144, v176
	v_ashrrev_i32_e32 v145, 31, v144
	v_lshl_add_u64 v[144:145], v[144:145], 1, s[100:101]
	global_load_dwordx4 v[112:115], v[144:145], off
	global_load_dwordx4 v[116:119], v[144:145], off offset:32
	global_load_dwordx4 v[120:123], v[144:145], off offset:64
	global_load_dwordx4 v[124:127], v[144:145], off offset:96
	global_load_dwordx4 v[128:131], v[144:145], off offset:128
	global_load_dwordx4 v[132:135], v[144:145], off offset:160
	global_load_dwordx4 v[136:139], v[144:145], off offset:192
	global_load_dwordx4 v[140:143], v[144:145], off offset:224
	s_and_saveexec_b64 s[36:37], s[20:21]
	s_cbranch_execz .LBB0_1486
	global_load_dword v2, v[174:175], off

.LBB0_1500:
	s_or_b64 exec, exec, s[36:37]
	s_waitcnt vmcnt(0)
	v_add_f32_e32 v2, 0, v2
	v_add_f32_e32 v3, v2, v1
	v_add_f32_e32 v8, v3, v5
	v_add_f32_e32 v9, v8, v4
	v_add_f32_e32 v6, v9, v6
	v_add_f32_e32 v7, v6, v7
	v_add_f32_e32 v4, v7, v11
	v_add_f32_e32 v5, v4, v10
	ds_bpermute_b32 v1, v190, v5
	s_waitcnt lgkmcnt(0)
	v_add_f32_e32 v1, v5, v1
	v_cndmask_b32_e64 v1, v1, v5, s[8:9]
	ds_bpermute_b32 v10, v191, v1
	s_waitcnt lgkmcnt(0)
	v_add_f32_e32 v10, v1, v10
	v_cndmask_b32_e64 v1, v10, v1, s[10:11]
	ds_bpermute_b32 v10, v192, v1
	s_waitcnt lgkmcnt(0)
	v_add_f32_e32 v10, v1, v10
	v_cndmask_b32_e64 v1, v10, v1, s[12:13]
	ds_bpermute_b32 v10, v193, v1
	s_waitcnt lgkmcnt(0)
	v_add_f32_e32 v10, v1, v10
	v_cndmask_b32_e64 v1, v10, v1, s[14:15]
	ds_bpermute_b32 v10, v194, v1
	s_waitcnt lgkmcnt(0)
	v_add_f32_e32 v10, v1, v10
	v_cndmask_b32_e64 v1, v10, v1, s[16:17]
	ds_bpermute_b32 v10, v195, v1
	s_waitcnt lgkmcnt(0)
	v_add_f32_e32 v10, v1, v10
	s_and_saveexec_b64 s[36:37], s[0:1]
	v_mov_b32_e32 v11, s51
	ds_write_b32 v11, v10
	s_or_b64 exec, exec, s[36:37]
	v_cndmask_b32_e64 v1, v10, v1, s[18:19]
	s_andn2_b64 vcc, exec, s[24:25]
	v_sub_f32_e32 v10, v1, v5
	s_waitcnt lgkmcnt(0)
	s_barrier
	s_cbranch_vccnz .LBB0_1505
	s_add_i32 s26, 0, 0x1c800
	s_mov_b32 s36, s33

.LBB0_1507:
	s_or_b64 exec, exec, s[38:39]
	s_lshr_b32 s78, s84, 6
	s_add_i32 s79, s78, 4
	s_add_u32 s38, s76, s84
	s_addc_u32 s39, s77, 0
	s_lshl_b64 s[20:21], s[38:39], 11
	s_lshl_b64 s[38:39], s[38:39], 12
	v_mov_b32_e32 v2, v176
	s_add_u32 s38, s65, s38
	s_addc_u32 s39, s66, s39
	v_ashrrev_i32_e32 v3, 31, v2
	v_lshl_add_u64 v[2:3], v[2:3], 1, s[38:39]
	v_mov_b32_e32 v14, v0
	v_mov_b32_e32 v15, v0
	s_waitcnt vmcnt(0)
	v_add_u32_e32 v201, s84, v198
	v_mov_b32_e32 v1, v0
	v_mov_b32_e32 v2, v0
	v_mov_b32_e32 v3, v0
	v_mov_b32_e32 v4, v0
	v_mov_b32_e32 v5, v0
	v_mov_b32_e32 v6, v0
	v_mov_b32_e32 v7, v0
	v_mov_b32_e32 v8, v0
	v_mov_b32_e32 v9, v0
	v_mov_b32_e32 v10, v0
	v_mov_b32_e32 v11, v0
	v_mov_b32_e32 v12, v0
	v_mov_b32_e32 v13, v0
	s_add_i32 s84, s84, s52
	v_mov_b64_e32 v[62:63], v[14:15]
	v_mov_b64_e32 v[78:79], v[14:15]
	v_mov_b64_e32 v[94:95], v[14:15]
	v_mov_b64_e32 v[110:111], v[14:15]
	s_mov_b32 s80, 0
	v_mov_b32_e32 v204, 0
	v_mov_b32_e32 v202, 0xf149f2ca
	s_mov_b32 s82, 2
	s_mov_b32 s81, -4
	s_mov_b32 s83, 63
	v_mov_b32_e32 v203, v199
	s_or_b32 s85, s78, 3
	s_or_b32 s86, s84, 31
	v_mov_b64_e32 v[60:61], v[12:13]
	v_mov_b64_e32 v[58:59], v[10:11]
	v_mov_b64_e32 v[56:57], v[8:9]
	v_mov_b64_e32 v[54:55], v[6:7]
	v_mov_b64_e32 v[52:53], v[4:5]
	v_mov_b64_e32 v[50:51], v[2:3]
	v_mov_b64_e32 v[48:49], v[0:1]
	v_mov_b64_e32 v[76:77], v[12:13]
	v_mov_b64_e32 v[74:75], v[10:11]
	v_mov_b64_e32 v[72:73], v[8:9]
	v_mov_b64_e32 v[70:71], v[6:7]
	v_mov_b64_e32 v[68:69], v[4:5]
	v_mov_b64_e32 v[66:67], v[2:3]
	v_mov_b64_e32 v[64:65], v[0:1]
	v_mov_b64_e32 v[92:93], v[12:13]
	v_mov_b64_e32 v[90:91], v[10:11]
	v_mov_b64_e32 v[88:89], v[8:9]
	v_mov_b64_e32 v[86:87], v[6:7]
	v_mov_b64_e32 v[84:85], v[4:5]
	v_mov_b64_e32 v[82:83], v[2:3]
	v_mov_b64_e32 v[80:81], v[0:1]
	v_mov_b64_e32 v[108:109], v[12:13]
	v_mov_b64_e32 v[106:107], v[10:11]
	v_mov_b64_e32 v[104:105], v[8:9]
	v_mov_b64_e32 v[102:103], v[6:7]
	v_mov_b64_e32 v[100:101], v[4:5]
	v_mov_b64_e32 v[98:99], v[2:3]
	v_mov_b64_e32 v[96:97], v[0:1]
	s_waitcnt vmcnt(7)
	s_waitcnt vmcnt(6)
	s_waitcnt vmcnt(5)
	s_waitcnt vmcnt(4)
	s_waitcnt vmcnt(3)
	s_waitcnt vmcnt(2)
	s_waitcnt vmcnt(1)
	s_waitcnt vmcnt(0)
	s_waitcnt lgkmcnt(0)
	s_barrier
	s_branch .LBB0_1511
